# P6 epilogue: full 128-byte-line loads/stores via DPP row_ror:8 exchange of the two 16-byte row pieces between lanes fr and fr^8 (8 rows x 128 B per instruction instead of 16 rows x 64 B)
# speedup vs baseline: 1.0070x; 1.0070x over previous
;     __device__ __forceinline__ void operator()(const f32x4 (&acc)[2][2][4][2], const Unit& u, int wr, int wc, int fr, int fq) const {
;         const int col0 = u.pn * 256 + wc * 32 + 8 * fq, rowbase = u.pm * 256 + wr * 64 + fr;
; #pragma unroll
;         for (int ai = 0; ai < 2; ++ai)
; #pragma unroll
;             for (int m = 0; m < 4; ++m) {
;                 const int row = rowbase + ai * 128 + m * 16; const size_t off = (size_t)row * DM + col0;
;                 float q = 0.f;
; #pragma unroll
;                 for (int bj = 0; bj < 2; ++bj) {
;                     const f32x4 r0 = *(const f32x4*)(resid + off + bj * 128), r1 = *(const f32x4*)(resid + off + bj * 128 + 4);
;                     const f32x4 o0 = r0 + acc[ai][bj][m][0], o1 = r1 + acc[ai][bj][m][1];
;                     *(f32x4*)(out + off + bj * 128) = o0; *(f32x4*)(out + off + bj * 128 + 4) = o1;
.LBB0_996:
	v_lshl_add_u32 v162, s34, 8, v146
	v_lshl_or_b32 v160, s50, 8, v148
	v_lshl_add_u32 v144, v162, 10, v160
	v_lshlrev_b32_e32 v144, 2, v144
	v_mbcnt_lo_u32_b32 v145, -1, 0
	v_mbcnt_hi_u32_b32 v145, -1, v145
	v_and_b32_e32 v145, 8, v145
	v_mul_i32_i24_e32 v145, 0xfffff002, v145
	v_add_u32_e32 v232, v144, v145
	s_andn2_b64 vcc, exec, s[0:1]
	s_mov_b64 s[0:1], -1
	v_add_u32_e32 v233, 0x10000, v232
	v_add_u32_e32 v234, 0x20000, v232
	v_add_u32_e32 v235, 0x30000, v232
	v_add_u32_e32 v236, 0x80000, v232
	v_add_u32_e32 v237, 0x90000, v232
	v_add_u32_e32 v238, 0xa0000, v232
	v_add_u32_e32 v239, 0xb0000, v232
	v_add_u32_e32 v240, 0x8000, v232
	v_add_u32_e32 v241, 0x8000, v233
	v_add_u32_e32 v242, 0x8000, v234
	v_add_u32_e32 v243, 0x8000, v235
	v_add_u32_e32 v244, 0x8000, v236
	v_add_u32_e32 v245, 0x8000, v237
	v_add_u32_e32 v246, 0x8000, v238
	v_add_u32_e32 v247, 0x8000, v239
	global_load_dwordx4 v[152:155], v232, s[54:55]
	global_load_dwordx4 v[156:159], v240, s[54:55]
	global_load_dwordx4 v[160:163], v232, s[54:55] offset:512
	global_load_dwordx4 v[164:167], v240, s[54:55] offset:512
	global_load_dwordx4 v[168:171], v233, s[54:55]
	global_load_dwordx4 v[172:175], v241, s[54:55]
	global_load_dwordx4 v[176:179], v233, s[54:55] offset:512
	global_load_dwordx4 v[180:183], v241, s[54:55] offset:512
	global_load_dwordx4 v[184:187], v234, s[54:55]
	global_load_dwordx4 v[188:191], v242, s[54:55]
	global_load_dwordx4 v[192:195], v234, s[54:55] offset:512
	global_load_dwordx4 v[196:199], v242, s[54:55] offset:512
	global_load_dwordx4 v[200:203], v235, s[54:55]
	global_load_dwordx4 v[204:207], v243, s[54:55]
	global_load_dwordx4 v[208:211], v235, s[54:55] offset:512
	global_load_dwordx4 v[212:215], v243, s[54:55] offset:512
	global_load_dwordx4 v[216:219], v236, s[54:55]
	global_load_dwordx4 v[220:223], v244, s[54:55]
	global_load_dwordx4 v[224:227], v236, s[54:55] offset:512
	global_load_dwordx4 v[228:231], v244, s[54:55] offset:512
	v_mov_b32_dpp v248, v120 row_ror:8 row_mask:0xf bank_mask:0xf
	v_mov_b32_dpp v249, v121 row_ror:8 row_mask:0xf bank_mask:0xf
	v_mov_b32_dpp v250, v122 row_ror:8 row_mask:0xf bank_mask:0xf
	v_mov_b32_dpp v251, v123 row_ror:8 row_mask:0xf bank_mask:0xf
	v_mov_b32_dpp v120, v124 row_ror:8 row_mask:0xf bank_mask:0x3
	v_mov_b32_dpp v121, v125 row_ror:8 row_mask:0xf bank_mask:0x3
	v_mov_b32_dpp v122, v126 row_ror:8 row_mask:0xf bank_mask:0x3
	v_mov_b32_dpp v123, v127 row_ror:8 row_mask:0xf bank_mask:0x3
	v_mov_b32_dpp v124, v248 quad_perm:[0,1,2,3] row_mask:0xf bank_mask:0xc
	v_mov_b32_dpp v125, v249 quad_perm:[0,1,2,3] row_mask:0xf bank_mask:0xc
	v_mov_b32_dpp v126, v250 quad_perm:[0,1,2,3] row_mask:0xf bank_mask:0xc
	v_mov_b32_dpp v127, v251 quad_perm:[0,1,2,3] row_mask:0xf bank_mask:0xc
	s_waitcnt vmcnt(18)
	v_pk_add_f32 v[124:125], v[124:125], v[152:153]
	v_pk_add_f32 v[126:127], v[126:127], v[154:155]
	v_pk_add_f32 v[120:121], v[120:121], v[156:157]
	v_pk_add_f32 v[122:123], v[122:123], v[158:159]
	global_store_dwordx4 v232, v[124:127], s[48:49]
	global_store_dwordx4 v240, v[120:123], s[48:49]
	v_mov_b32_dpp v248, v104 row_ror:8 row_mask:0xf bank_mask:0xf
	v_mov_b32_dpp v249, v105 row_ror:8 row_mask:0xf bank_mask:0xf
	v_mov_b32_dpp v250, v106 row_ror:8 row_mask:0xf bank_mask:0xf
	v_mov_b32_dpp v251, v107 row_ror:8 row_mask:0xf bank_mask:0xf
	v_mov_b32_dpp v104, v112 row_ror:8 row_mask:0xf bank_mask:0x3
	v_mov_b32_dpp v105, v113 row_ror:8 row_mask:0xf bank_mask:0x3
	v_mov_b32_dpp v106, v114 row_ror:8 row_mask:0xf bank_mask:0x3
	v_mov_b32_dpp v107, v115 row_ror:8 row_mask:0xf bank_mask:0x3
	v_mov_b32_dpp v112, v248 quad_perm:[0,1,2,3] row_mask:0xf bank_mask:0xc
	v_mov_b32_dpp v113, v249 quad_perm:[0,1,2,3] row_mask:0xf bank_mask:0xc
	v_mov_b32_dpp v114, v250 quad_perm:[0,1,2,3] row_mask:0xf bank_mask:0xc
	v_mov_b32_dpp v115, v251 quad_perm:[0,1,2,3] row_mask:0xf bank_mask:0xc
	s_waitcnt vmcnt(18)
	v_pk_add_f32 v[112:113], v[112:113], v[160:161]
	v_pk_add_f32 v[114:115], v[114:115], v[162:163]
	v_pk_add_f32 v[104:105], v[104:105], v[164:165]
	v_pk_add_f32 v[106:107], v[106:107], v[166:167]
	global_store_dwordx4 v232, v[112:115], s[48:49] offset:512
	global_store_dwordx4 v240, v[104:107], s[48:49] offset:512
	v_mov_b32_dpp v248, v108 row_ror:8 row_mask:0xf bank_mask:0xf
	v_mov_b32_dpp v249, v109 row_ror:8 row_mask:0xf bank_mask:0xf
	v_mov_b32_dpp v250, v110 row_ror:8 row_mask:0xf bank_mask:0xf
	v_mov_b32_dpp v251, v111 row_ror:8 row_mask:0xf bank_mask:0xf
	v_mov_b32_dpp v108, v116 row_ror:8 row_mask:0xf bank_mask:0x3
	v_mov_b32_dpp v109, v117 row_ror:8 row_mask:0xf bank_mask:0x3
	v_mov_b32_dpp v110, v118 row_ror:8 row_mask:0xf bank_mask:0x3
	v_mov_b32_dpp v111, v119 row_ror:8 row_mask:0xf bank_mask:0x3
	v_mov_b32_dpp v116, v248 quad_perm:[0,1,2,3] row_mask:0xf bank_mask:0xc
	v_mov_b32_dpp v117, v249 quad_perm:[0,1,2,3] row_mask:0xf bank_mask:0xc
	v_mov_b32_dpp v118, v250 quad_perm:[0,1,2,3] row_mask:0xf bank_mask:0xc
	v_mov_b32_dpp v119, v251 quad_perm:[0,1,2,3] row_mask:0xf bank_mask:0xc
	s_waitcnt vmcnt(18)
	v_pk_add_f32 v[116:117], v[116:117], v[168:169]
	v_pk_add_f32 v[118:119], v[118:119], v[170:171]
	v_pk_add_f32 v[108:109], v[108:109], v[172:173]
	v_pk_add_f32 v[110:111], v[110:111], v[174:175]
	global_store_dwordx4 v233, v[116:119], s[48:49]
	global_store_dwordx4 v241, v[108:111], s[48:49]
	v_mov_b32_dpp v248, v88 row_ror:8 row_mask:0xf bank_mask:0xf
	v_mov_b32_dpp v249, v89 row_ror:8 row_mask:0xf bank_mask:0xf
	v_mov_b32_dpp v250, v90 row_ror:8 row_mask:0xf bank_mask:0xf
	v_mov_b32_dpp v251, v91 row_ror:8 row_mask:0xf bank_mask:0xf
	v_mov_b32_dpp v88, v96 row_ror:8 row_mask:0xf bank_mask:0x3
	v_mov_b32_dpp v89, v97 row_ror:8 row_mask:0xf bank_mask:0x3
	v_mov_b32_dpp v90, v98 row_ror:8 row_mask:0xf bank_mask:0x3
	v_mov_b32_dpp v91, v99 row_ror:8 row_mask:0xf bank_mask:0x3
	v_mov_b32_dpp v96, v248 quad_perm:[0,1,2,3] row_mask:0xf bank_mask:0xc
	v_mov_b32_dpp v97, v249 quad_perm:[0,1,2,3] row_mask:0xf bank_mask:0xc
	v_mov_b32_dpp v98, v250 quad_perm:[0,1,2,3] row_mask:0xf bank_mask:0xc
	v_mov_b32_dpp v99, v251 quad_perm:[0,1,2,3] row_mask:0xf bank_mask:0xc
	s_waitcnt vmcnt(18)
;     __device__ __forceinline__ void operator()(const f32x4 (&acc)[2][2][4][2], const Unit& u, int wr, int wc, int fr, int fq) const {
;         const int col0 = u.pn * 256 + wc * 32 + 8 * fq, rowbase = u.pm * 256 + wr * 64 + fr;
; #pragma unroll
;         for (int ai = 0; ai < 2; ++ai)
; #pragma unroll
;             for (int m = 0; m < 4; ++m) {
;                 const int row = rowbase + ai * 128 + m * 16; const size_t off = (size_t)row * DM + col0;
;                 float q = 0.f;
; #pragma unroll
;                 for (int bj = 0; bj < 2; ++bj) {
;                     const f32x4 r0 = *(const f32x4*)(resid + off + bj * 128), r1 = *(const f32x4*)(resid + off + bj * 128 + 4);
;                     const f32x4 o0 = r0 + acc[ai][bj][m][0], o1 = r1 + acc[ai][bj][m][1];
;                     *(f32x4*)(out + off + bj * 128) = o0; *(f32x4*)(out + off + bj * 128 + 4) = o1;
	v_pk_add_f32 v[96:97], v[96:97], v[176:177]
	v_pk_add_f32 v[98:99], v[98:99], v[178:179]
	v_pk_add_f32 v[88:89], v[88:89], v[180:181]
	v_pk_add_f32 v[90:91], v[90:91], v[182:183]
	global_store_dwordx4 v233, v[96:99], s[48:49] offset:512
	global_store_dwordx4 v241, v[88:91], s[48:49] offset:512
	v_mov_b32_dpp v248, v92 row_ror:8 row_mask:0xf bank_mask:0xf
	v_mov_b32_dpp v249, v93 row_ror:8 row_mask:0xf bank_mask:0xf
	v_mov_b32_dpp v250, v94 row_ror:8 row_mask:0xf bank_mask:0xf
	v_mov_b32_dpp v251, v95 row_ror:8 row_mask:0xf bank_mask:0xf
	v_mov_b32_dpp v92, v100 row_ror:8 row_mask:0xf bank_mask:0x3
	v_mov_b32_dpp v93, v101 row_ror:8 row_mask:0xf bank_mask:0x3
	v_mov_b32_dpp v94, v102 row_ror:8 row_mask:0xf bank_mask:0x3
	v_mov_b32_dpp v95, v103 row_ror:8 row_mask:0xf bank_mask:0x3
	v_mov_b32_dpp v100, v248 quad_perm:[0,1,2,3] row_mask:0xf bank_mask:0xc
	v_mov_b32_dpp v101, v249 quad_perm:[0,1,2,3] row_mask:0xf bank_mask:0xc
	v_mov_b32_dpp v102, v250 quad_perm:[0,1,2,3] row_mask:0xf bank_mask:0xc
	v_mov_b32_dpp v103, v251 quad_perm:[0,1,2,3] row_mask:0xf bank_mask:0xc
	s_waitcnt vmcnt(18)
	v_pk_add_f32 v[100:101], v[100:101], v[184:185]
	v_pk_add_f32 v[102:103], v[102:103], v[186:187]
	v_pk_add_f32 v[92:93], v[92:93], v[188:189]
	v_pk_add_f32 v[94:95], v[94:95], v[190:191]
	global_store_dwordx4 v234, v[100:103], s[48:49]
	global_store_dwordx4 v242, v[92:95], s[48:49]
	v_mov_b32_dpp v248, v72 row_ror:8 row_mask:0xf bank_mask:0xf
	v_mov_b32_dpp v249, v73 row_ror:8 row_mask:0xf bank_mask:0xf
	v_mov_b32_dpp v250, v74 row_ror:8 row_mask:0xf bank_mask:0xf
	v_mov_b32_dpp v251, v75 row_ror:8 row_mask:0xf bank_mask:0xf
	v_mov_b32_dpp v72, v80 row_ror:8 row_mask:0xf bank_mask:0x3
	v_mov_b32_dpp v73, v81 row_ror:8 row_mask:0xf bank_mask:0x3
	v_mov_b32_dpp v74, v82 row_ror:8 row_mask:0xf bank_mask:0x3
	v_mov_b32_dpp v75, v83 row_ror:8 row_mask:0xf bank_mask:0x3
	v_mov_b32_dpp v80, v248 quad_perm:[0,1,2,3] row_mask:0xf bank_mask:0xc
	v_mov_b32_dpp v81, v249 quad_perm:[0,1,2,3] row_mask:0xf bank_mask:0xc
	v_mov_b32_dpp v82, v250 quad_perm:[0,1,2,3] row_mask:0xf bank_mask:0xc
	v_mov_b32_dpp v83, v251 quad_perm:[0,1,2,3] row_mask:0xf bank_mask:0xc
	s_waitcnt vmcnt(18)
	v_pk_add_f32 v[80:81], v[80:81], v[192:193]
	v_pk_add_f32 v[82:83], v[82:83], v[194:195]
	v_pk_add_f32 v[72:73], v[72:73], v[196:197]
	v_pk_add_f32 v[74:75], v[74:75], v[198:199]
	global_store_dwordx4 v234, v[80:83], s[48:49] offset:512
	global_store_dwordx4 v242, v[72:75], s[48:49] offset:512
	global_load_dwordx4 v[152:155], v237, s[54:55]
	global_load_dwordx4 v[156:159], v245, s[54:55]
	global_load_dwordx4 v[160:163], v237, s[54:55] offset:512
	global_load_dwordx4 v[164:167], v245, s[54:55] offset:512
	global_load_dwordx4 v[168:171], v238, s[54:55]
	global_load_dwordx4 v[172:175], v246, s[54:55]
	global_load_dwordx4 v[176:179], v238, s[54:55] offset:512
	global_load_dwordx4 v[180:183], v246, s[54:55] offset:512
	global_load_dwordx4 v[184:187], v239, s[54:55]
	global_load_dwordx4 v[188:191], v247, s[54:55]
	global_load_dwordx4 v[192:195], v239, s[54:55] offset:512
	global_load_dwordx4 v[196:199], v247, s[54:55] offset:512
	v_mov_b32_dpp v248, v76 row_ror:8 row_mask:0xf bank_mask:0xf
	v_mov_b32_dpp v249, v77 row_ror:8 row_mask:0xf bank_mask:0xf
	v_mov_b32_dpp v250, v78 row_ror:8 row_mask:0xf bank_mask:0xf
	v_mov_b32_dpp v251, v79 row_ror:8 row_mask:0xf bank_mask:0xf
	v_mov_b32_dpp v76, v84 row_ror:8 row_mask:0xf bank_mask:0x3
	v_mov_b32_dpp v77, v85 row_ror:8 row_mask:0xf bank_mask:0x3
	v_mov_b32_dpp v78, v86 row_ror:8 row_mask:0xf bank_mask:0x3
	v_mov_b32_dpp v79, v87 row_ror:8 row_mask:0xf bank_mask:0x3
	v_mov_b32_dpp v84, v248 quad_perm:[0,1,2,3] row_mask:0xf bank_mask:0xc
	v_mov_b32_dpp v85, v249 quad_perm:[0,1,2,3] row_mask:0xf bank_mask:0xc
	v_mov_b32_dpp v86, v250 quad_perm:[0,1,2,3] row_mask:0xf bank_mask:0xc
	v_mov_b32_dpp v87, v251 quad_perm:[0,1,2,3] row_mask:0xf bank_mask:0xc
	s_waitcnt vmcnt(30)
	v_pk_add_f32 v[84:85], v[84:85], v[200:201]
	v_pk_add_f32 v[86:87], v[86:87], v[202:203]
	v_pk_add_f32 v[76:77], v[76:77], v[204:205]
	v_pk_add_f32 v[78:79], v[78:79], v[206:207]
	global_store_dwordx4 v235, v[84:87], s[48:49]
	global_store_dwordx4 v243, v[76:79], s[48:49]
	v_mov_b32_dpp v248, v64 row_ror:8 row_mask:0xf bank_mask:0xf
	v_mov_b32_dpp v249, v65 row_ror:8 row_mask:0xf bank_mask:0xf
	v_mov_b32_dpp v250, v66 row_ror:8 row_mask:0xf bank_mask:0xf
	v_mov_b32_dpp v251, v67 row_ror:8 row_mask:0xf bank_mask:0xf
	v_mov_b32_dpp v64, v68 row_ror:8 row_mask:0xf bank_mask:0x3
	v_mov_b32_dpp v65, v69 row_ror:8 row_mask:0xf bank_mask:0x3
	v_mov_b32_dpp v66, v70 row_ror:8 row_mask:0xf bank_mask:0x3
	v_mov_b32_dpp v67, v71 row_ror:8 row_mask:0xf bank_mask:0x3
	v_mov_b32_dpp v68, v248 quad_perm:[0,1,2,3] row_mask:0xf bank_mask:0xc
	v_mov_b32_dpp v69, v249 quad_perm:[0,1,2,3] row_mask:0xf bank_mask:0xc
	v_mov_b32_dpp v70, v250 quad_perm:[0,1,2,3] row_mask:0xf bank_mask:0xc
	v_mov_b32_dpp v71, v251 quad_perm:[0,1,2,3] row_mask:0xf bank_mask:0xc
	s_waitcnt vmcnt(30)
	v_pk_add_f32 v[68:69], v[68:69], v[208:209]
	v_pk_add_f32 v[70:71], v[70:71], v[210:211]
	v_pk_add_f32 v[64:65], v[64:65], v[212:213]
	v_pk_add_f32 v[66:67], v[66:67], v[214:215]
	global_store_dwordx4 v235, v[68:71], s[48:49] offset:512
	global_store_dwordx4 v243, v[64:67], s[48:49] offset:512
	v_mov_b32_dpp v248, v56 row_ror:8 row_mask:0xf bank_mask:0xf
	v_mov_b32_dpp v249, v57 row_ror:8 row_mask:0xf bank_mask:0xf
	v_mov_b32_dpp v250, v58 row_ror:8 row_mask:0xf bank_mask:0xf
	v_mov_b32_dpp v251, v59 row_ror:8 row_mask:0xf bank_mask:0xf
	v_mov_b32_dpp v56, v60 row_ror:8 row_mask:0xf bank_mask:0x3
	v_mov_b32_dpp v57, v61 row_ror:8 row_mask:0xf bank_mask:0x3
	v_mov_b32_dpp v58, v62 row_ror:8 row_mask:0xf bank_mask:0x3
	v_mov_b32_dpp v59, v63 row_ror:8 row_mask:0xf bank_mask:0x3
	v_mov_b32_dpp v60, v248 quad_perm:[0,1,2,3] row_mask:0xf bank_mask:0xc
	v_mov_b32_dpp v61, v249 quad_perm:[0,1,2,3] row_mask:0xf bank_mask:0xc
	v_mov_b32_dpp v62, v250 quad_perm:[0,1,2,3] row_mask:0xf bank_mask:0xc
	v_mov_b32_dpp v63, v251 quad_perm:[0,1,2,3] row_mask:0xf bank_mask:0xc
	s_waitcnt vmcnt(30)
;     __device__ __forceinline__ void operator()(const f32x4 (&acc)[2][2][4][2], const Unit& u, int wr, int wc, int fr, int fq) const {
;         const int col0 = u.pn * 256 + wc * 32 + 8 * fq, rowbase = u.pm * 256 + wr * 64 + fr;
; #pragma unroll
;         for (int ai = 0; ai < 2; ++ai)
; #pragma unroll
;             for (int m = 0; m < 4; ++m) {
;                 const int row = rowbase + ai * 128 + m * 16; const size_t off = (size_t)row * DM + col0;
;                 float q = 0.f;
; #pragma unroll
;                 for (int bj = 0; bj < 2; ++bj) {
;                     const f32x4 r0 = *(const f32x4*)(resid + off + bj * 128), r1 = *(const f32x4*)(resid + off + bj * 128 + 4);
;                     const f32x4 o0 = r0 + acc[ai][bj][m][0], o1 = r1 + acc[ai][bj][m][1];
;                     *(f32x4*)(out + off + bj * 128) = o0; *(f32x4*)(out + off + bj * 128 + 4) = o1;
	v_pk_add_f32 v[60:61], v[60:61], v[216:217]
	v_pk_add_f32 v[62:63], v[62:63], v[218:219]
	v_pk_add_f32 v[56:57], v[56:57], v[220:221]
	v_pk_add_f32 v[58:59], v[58:59], v[222:223]
	global_store_dwordx4 v236, v[60:63], s[48:49]
	global_store_dwordx4 v244, v[56:59], s[48:49]
	v_mov_b32_dpp v248, v40 row_ror:8 row_mask:0xf bank_mask:0xf
	v_mov_b32_dpp v249, v41 row_ror:8 row_mask:0xf bank_mask:0xf
	v_mov_b32_dpp v250, v42 row_ror:8 row_mask:0xf bank_mask:0xf
	v_mov_b32_dpp v251, v43 row_ror:8 row_mask:0xf bank_mask:0xf
	v_mov_b32_dpp v40, v48 row_ror:8 row_mask:0xf bank_mask:0x3
	v_mov_b32_dpp v41, v49 row_ror:8 row_mask:0xf bank_mask:0x3
	v_mov_b32_dpp v42, v50 row_ror:8 row_mask:0xf bank_mask:0x3
	v_mov_b32_dpp v43, v51 row_ror:8 row_mask:0xf bank_mask:0x3
	v_mov_b32_dpp v48, v248 quad_perm:[0,1,2,3] row_mask:0xf bank_mask:0xc
	v_mov_b32_dpp v49, v249 quad_perm:[0,1,2,3] row_mask:0xf bank_mask:0xc
	v_mov_b32_dpp v50, v250 quad_perm:[0,1,2,3] row_mask:0xf bank_mask:0xc
	v_mov_b32_dpp v51, v251 quad_perm:[0,1,2,3] row_mask:0xf bank_mask:0xc
	s_waitcnt vmcnt(30)
	v_pk_add_f32 v[48:49], v[48:49], v[224:225]
	v_pk_add_f32 v[50:51], v[50:51], v[226:227]
	v_pk_add_f32 v[40:41], v[40:41], v[228:229]
	v_pk_add_f32 v[42:43], v[42:43], v[230:231]
	global_store_dwordx4 v236, v[48:51], s[48:49] offset:512
	global_store_dwordx4 v244, v[40:43], s[48:49] offset:512
	v_mov_b32_dpp v248, v44 row_ror:8 row_mask:0xf bank_mask:0xf
	v_mov_b32_dpp v249, v45 row_ror:8 row_mask:0xf bank_mask:0xf
	v_mov_b32_dpp v250, v46 row_ror:8 row_mask:0xf bank_mask:0xf
	v_mov_b32_dpp v251, v47 row_ror:8 row_mask:0xf bank_mask:0xf
	v_mov_b32_dpp v44, v52 row_ror:8 row_mask:0xf bank_mask:0x3
	v_mov_b32_dpp v45, v53 row_ror:8 row_mask:0xf bank_mask:0x3
	v_mov_b32_dpp v46, v54 row_ror:8 row_mask:0xf bank_mask:0x3
	v_mov_b32_dpp v47, v55 row_ror:8 row_mask:0xf bank_mask:0x3
	v_mov_b32_dpp v52, v248 quad_perm:[0,1,2,3] row_mask:0xf bank_mask:0xc
	v_mov_b32_dpp v53, v249 quad_perm:[0,1,2,3] row_mask:0xf bank_mask:0xc
	v_mov_b32_dpp v54, v250 quad_perm:[0,1,2,3] row_mask:0xf bank_mask:0xc
	v_mov_b32_dpp v55, v251 quad_perm:[0,1,2,3] row_mask:0xf bank_mask:0xc
	s_waitcnt vmcnt(18)
	v_pk_add_f32 v[52:53], v[52:53], v[152:153]
	v_pk_add_f32 v[54:55], v[54:55], v[154:155]
	v_pk_add_f32 v[44:45], v[44:45], v[156:157]
	v_pk_add_f32 v[46:47], v[46:47], v[158:159]
	global_store_dwordx4 v237, v[52:55], s[48:49]
	global_store_dwordx4 v245, v[44:47], s[48:49]
	v_mov_b32_dpp v248, v24 row_ror:8 row_mask:0xf bank_mask:0xf
	v_mov_b32_dpp v249, v25 row_ror:8 row_mask:0xf bank_mask:0xf
	v_mov_b32_dpp v250, v26 row_ror:8 row_mask:0xf bank_mask:0xf
	v_mov_b32_dpp v251, v27 row_ror:8 row_mask:0xf bank_mask:0xf
	v_mov_b32_dpp v24, v32 row_ror:8 row_mask:0xf bank_mask:0x3
	v_mov_b32_dpp v25, v33 row_ror:8 row_mask:0xf bank_mask:0x3
	v_mov_b32_dpp v26, v34 row_ror:8 row_mask:0xf bank_mask:0x3
	v_mov_b32_dpp v27, v35 row_ror:8 row_mask:0xf bank_mask:0x3
	v_mov_b32_dpp v32, v248 quad_perm:[0,1,2,3] row_mask:0xf bank_mask:0xc
	v_mov_b32_dpp v33, v249 quad_perm:[0,1,2,3] row_mask:0xf bank_mask:0xc
	v_mov_b32_dpp v34, v250 quad_perm:[0,1,2,3] row_mask:0xf bank_mask:0xc
	v_mov_b32_dpp v35, v251 quad_perm:[0,1,2,3] row_mask:0xf bank_mask:0xc
	s_waitcnt vmcnt(18)
	v_pk_add_f32 v[32:33], v[32:33], v[160:161]
	v_pk_add_f32 v[34:35], v[34:35], v[162:163]
	v_pk_add_f32 v[24:25], v[24:25], v[164:165]
	v_pk_add_f32 v[26:27], v[26:27], v[166:167]
	global_store_dwordx4 v237, v[32:35], s[48:49] offset:512
	global_store_dwordx4 v245, v[24:27], s[48:49] offset:512
	v_mov_b32_dpp v248, v28 row_ror:8 row_mask:0xf bank_mask:0xf
	v_mov_b32_dpp v249, v29 row_ror:8 row_mask:0xf bank_mask:0xf
	v_mov_b32_dpp v250, v30 row_ror:8 row_mask:0xf bank_mask:0xf
	v_mov_b32_dpp v251, v31 row_ror:8 row_mask:0xf bank_mask:0xf
	v_mov_b32_dpp v28, v36 row_ror:8 row_mask:0xf bank_mask:0x3
	v_mov_b32_dpp v29, v37 row_ror:8 row_mask:0xf bank_mask:0x3
	v_mov_b32_dpp v30, v38 row_ror:8 row_mask:0xf bank_mask:0x3
	v_mov_b32_dpp v31, v39 row_ror:8 row_mask:0xf bank_mask:0x3
	v_mov_b32_dpp v36, v248 quad_perm:[0,1,2,3] row_mask:0xf bank_mask:0xc
	v_mov_b32_dpp v37, v249 quad_perm:[0,1,2,3] row_mask:0xf bank_mask:0xc
	v_mov_b32_dpp v38, v250 quad_perm:[0,1,2,3] row_mask:0xf bank_mask:0xc
	v_mov_b32_dpp v39, v251 quad_perm:[0,1,2,3] row_mask:0xf bank_mask:0xc
	s_waitcnt vmcnt(18)
; #define PG8_BAR __builtin_amdgcn_s_barrier()
; template <class Epi, class Sched, bool ALIGN_EPI = false, bool SP2 = false>
; __device__ __forceinline__ void gemm_phase(PG8_LAS unsigned char* lds, const Gemm g, const Sched& S, const Epi& E) {
;     ...
;         if (!has_next) break;
; #pragma unroll
;         for (int a = 0; a < 2; ++a)
; #pragma unroll
;             for (int b = 0; b < 2; ++b)
; #pragma unroll
;                 for (int m = 0; m < 4; ++m)
; #pragma unroll
;                     for (int n = 0; n < 2; ++n) acc[a][b][m][n] = (f32x4){0.f, 0.f, 0.f, 0.f};
;         cur = nxt; cA = nA; cB = nB; ++ui;
;         if constexpr (ALIGN_EPI) { if (wr == 1) PG8_BAR; }
;     __device__ __forceinline__ void operator()(const f32x4 (&acc)[2][2][4][2], const Unit& u, int wr, int wc, int fr, int fq) const {
;         const int col0 = u.pn * 256 + wc * 32 + 8 * fq, rowbase = u.pm * 256 + wr * 64 + fr;
; #pragma unroll
;         for (int ai = 0; ai < 2; ++ai)
; #pragma unroll
;             for (int m = 0; m < 4; ++m) {
;                 const int row = rowbase + ai * 128 + m * 16; const size_t off = (size_t)row * DM + col0;
;                 float q = 0.f;
; #pragma unroll
;                 for (int bj = 0; bj < 2; ++bj) {
;                     const f32x4 r0 = *(const f32x4*)(resid + off + bj * 128), r1 = *(const f32x4*)(resid + off + bj * 128 + 4);
;                     const f32x4 o0 = r0 + acc[ai][bj][m][0], o1 = r1 + acc[ai][bj][m][1];
;                     *(f32x4*)(out + off + bj * 128) = o0; *(f32x4*)(out + off + bj * 128 + 4) = o1;
	v_pk_add_f32 v[36:37], v[36:37], v[168:169]
	v_pk_add_f32 v[38:39], v[38:39], v[170:171]
	v_pk_add_f32 v[28:29], v[28:29], v[172:173]
	v_pk_add_f32 v[30:31], v[30:31], v[174:175]
	global_store_dwordx4 v238, v[36:39], s[48:49]
	global_store_dwordx4 v246, v[28:31], s[48:49]
	v_mov_b32_dpp v248, v8 row_ror:8 row_mask:0xf bank_mask:0xf
	v_mov_b32_dpp v249, v9 row_ror:8 row_mask:0xf bank_mask:0xf
	v_mov_b32_dpp v250, v10 row_ror:8 row_mask:0xf bank_mask:0xf
	v_mov_b32_dpp v251, v11 row_ror:8 row_mask:0xf bank_mask:0xf
	v_mov_b32_dpp v8, v16 row_ror:8 row_mask:0xf bank_mask:0x3
	v_mov_b32_dpp v9, v17 row_ror:8 row_mask:0xf bank_mask:0x3
	v_mov_b32_dpp v10, v18 row_ror:8 row_mask:0xf bank_mask:0x3
	v_mov_b32_dpp v11, v19 row_ror:8 row_mask:0xf bank_mask:0x3
	v_mov_b32_dpp v16, v248 quad_perm:[0,1,2,3] row_mask:0xf bank_mask:0xc
	v_mov_b32_dpp v17, v249 quad_perm:[0,1,2,3] row_mask:0xf bank_mask:0xc
	v_mov_b32_dpp v18, v250 quad_perm:[0,1,2,3] row_mask:0xf bank_mask:0xc
	v_mov_b32_dpp v19, v251 quad_perm:[0,1,2,3] row_mask:0xf bank_mask:0xc
	s_waitcnt vmcnt(18)
	v_pk_add_f32 v[16:17], v[16:17], v[176:177]
	v_pk_add_f32 v[18:19], v[18:19], v[178:179]
	v_pk_add_f32 v[8:9], v[8:9], v[180:181]
	v_pk_add_f32 v[10:11], v[10:11], v[182:183]
	global_store_dwordx4 v238, v[16:19], s[48:49] offset:512
	global_store_dwordx4 v246, v[8:11], s[48:49] offset:512
	v_mov_b32_dpp v248, v12 row_ror:8 row_mask:0xf bank_mask:0xf
	v_mov_b32_dpp v249, v13 row_ror:8 row_mask:0xf bank_mask:0xf
	v_mov_b32_dpp v250, v14 row_ror:8 row_mask:0xf bank_mask:0xf
	v_mov_b32_dpp v251, v15 row_ror:8 row_mask:0xf bank_mask:0xf
	v_mov_b32_dpp v12, v20 row_ror:8 row_mask:0xf bank_mask:0x3
	v_mov_b32_dpp v13, v21 row_ror:8 row_mask:0xf bank_mask:0x3
	v_mov_b32_dpp v14, v22 row_ror:8 row_mask:0xf bank_mask:0x3
	v_mov_b32_dpp v15, v23 row_ror:8 row_mask:0xf bank_mask:0x3
	v_mov_b32_dpp v20, v248 quad_perm:[0,1,2,3] row_mask:0xf bank_mask:0xc
	v_mov_b32_dpp v21, v249 quad_perm:[0,1,2,3] row_mask:0xf bank_mask:0xc
	v_mov_b32_dpp v22, v250 quad_perm:[0,1,2,3] row_mask:0xf bank_mask:0xc
	v_mov_b32_dpp v23, v251 quad_perm:[0,1,2,3] row_mask:0xf bank_mask:0xc
	s_waitcnt vmcnt(18)
	v_pk_add_f32 v[20:21], v[20:21], v[184:185]
	v_pk_add_f32 v[22:23], v[22:23], v[186:187]
	v_pk_add_f32 v[12:13], v[12:13], v[188:189]
	v_pk_add_f32 v[14:15], v[14:15], v[190:191]
	global_store_dwordx4 v239, v[20:23], s[48:49]
	global_store_dwordx4 v247, v[12:15], s[48:49]
	v_mov_b32_dpp v248, v0 row_ror:8 row_mask:0xf bank_mask:0xf
	v_mov_b32_dpp v249, v1 row_ror:8 row_mask:0xf bank_mask:0xf
	v_mov_b32_dpp v250, v2 row_ror:8 row_mask:0xf bank_mask:0xf
	v_mov_b32_dpp v251, v3 row_ror:8 row_mask:0xf bank_mask:0xf
	v_mov_b32_dpp v0, v4 row_ror:8 row_mask:0xf bank_mask:0x3
	v_mov_b32_dpp v1, v5 row_ror:8 row_mask:0xf bank_mask:0x3
	v_mov_b32_dpp v2, v6 row_ror:8 row_mask:0xf bank_mask:0x3
	v_mov_b32_dpp v3, v7 row_ror:8 row_mask:0xf bank_mask:0x3
	v_mov_b32_dpp v4, v248 quad_perm:[0,1,2,3] row_mask:0xf bank_mask:0xc
	v_mov_b32_dpp v5, v249 quad_perm:[0,1,2,3] row_mask:0xf bank_mask:0xc
	v_mov_b32_dpp v6, v250 quad_perm:[0,1,2,3] row_mask:0xf bank_mask:0xc
	v_mov_b32_dpp v7, v251 quad_perm:[0,1,2,3] row_mask:0xf bank_mask:0xc
	s_waitcnt vmcnt(18)
	v_pk_add_f32 v[4:5], v[4:5], v[192:193]
	v_pk_add_f32 v[6:7], v[6:7], v[194:195]
	v_pk_add_f32 v[0:1], v[0:1], v[196:197]
	v_pk_add_f32 v[2:3], v[2:3], v[198:199]
	global_store_dwordx4 v239, v[4:7], s[48:49] offset:512
	global_store_dwordx4 v247, v[0:3], s[48:49] offset:512
	s_cbranch_vccnz .LBB0_985
	s_andn2_b64 vcc, exec, s[4:5]
	s_cbranch_vccnz .LBB0_984
	s_barrier
	s_branch .LBB0_984
